# P GEMM: paired 128x128 tiles sharing the weight tile (double-buffered in spare LDS), EpiP written out for both tiles
# speedup vs baseline: 1.0751x; 1.0134x over previous
; DI bool xcd_tile(int bid, int G, int i, int MT, int NT, int& tm, int& tn) {
;   if ((G & 7) || (MT & 7)) { const int t = bid + i * G; if (t >= MT * NT) return false; tm = t / NT; tn = t % NT; return true; }
;   const int nbx = G >> 3, x = bid & 7, j = bid >> 3, MS = MT >> 3;
;   const int q = j + nbx * i;
;   if (q >= MS * NT) return false;
;   const int full = NT >> 3, wl = NT & 7;
;   int nb = q / (MS * 8), m, ni;
;   if (nb < full) { const int rem = q - nb * MS * 8; m = rem >> 3; ni = rem & 7; }
;   else { const int rem = q - full * MS * 8; nb = full; m = rem / wl; ni = rem % wl; }
;   tm = x * MS + m; tn = nb * 8 + ni;
;   return true;
; }
; template <int KSEL> DI void run_phase(const Params& p, int ph, char* lds) {
;     ...
;       for (int i = 0, tm, tn; xcd_tile(bid, G, i, 144, 26, tm, tn); ++i) gemm_tile(p.HY, DM, p.Win, DM, DM, tm * 128, tn * 128, lds, e);
.LBB0_663:
	s_andn2_b64 vcc, exec, s[0:1]
	s_cbranch_vccnz .LBB0_695
	s_cmp_lt_i32 s44, 1
	s_mov_b64 s[0:1], -1
	s_cbranch_scc1 .LBB0_693
	s_cmp_eq_u32 s44, 1
	s_cbranch_scc0 .LBB0_692
	s_mov_b32 s38, 0
	s_waitcnt vmcnt(0)
	s_branch .LBB0_669
.LBB0_668:
	s_and_b64 vcc, exec, s[2:3]
	s_cbranch_vccnz .LBB0_692
.LBB0_669:
	s_andn2_b64 vcc, exec, s[88:89]
	s_cbranch_vccnz .LBB0_673
	s_mul_i32 s28, s38, s52
	s_add_i32 s28, s28, s95
	s_mov_b64 s[2:3], 0
	s_cmpk_lt_i32 s28, 0x750
	s_mov_b64 s[0:1], 0
	s_cbranch_scc0 .LBB0_672
	s_mul_hi_i32 s0, s28, 0x4ec4ec4f
	s_lshr_b32 s1, s0, 31
	s_ashr_i32 s0, s0, 3
	s_add_i32 s26, s0, s1
	s_mul_i32 s0, s26, 26
	s_sub_i32 s27, s28, s0
	s_mov_b64 s[0:1], -1

; #define LAS __attribute__((address_space(3)))
; DI int opaque_tid() { int t = threadIdx.x; asm volatile("" : "+v"(t)); return t; }
; template <class Epi>
; DI void gemm_tile(const bf16_t* __restrict__ A, int lda, const bf16_t* __restrict__ Bt, int ldb, int K, int row0, int col0, char* lds, const Epi& epi) {
;   const int tid = opaque_tid(), lane = tid & 63, wid = tid >> 6, wr = wid >> 1, wc = wid & 1, fr = lane & 15, fq = lane >> 4;
;   const bf16_t* ag[4];
;   const bf16_t* bg[4];
; #pragma unroll
;   for (int i = 0; i < 4; ++i) {
;     const int id = i * 256 + tid, r = id >> 3, cp = id & 7, c = cp ^ ((r >> 1) & 7);
;     ag[i] = A + (size_t)(row0 + r) * lda + c * 8;
;     bg[i] = Bt + (size_t)(col0 + r) * ldb + c * 8;
;   }
;   f32x4 acc[4][4];
; #pragma unroll
;   for (int m = 0; m < 4; ++m)
; #pragma unroll
;     for (int n = 0; n < 4; ++n) acc[m][n] = (f32x4){0.f, 0.f, 0.f, 0.f};
;   const int KT = K >> 6;
;   auto stage_a = [&](int kt, int buf) {
;     char* sa = lds + buf * 32768;
; #pragma unroll
;     for (int i = 0; i < 4; ++i)
;       __builtin_amdgcn_global_load_lds((const void __attribute__((address_space(1)))*)(ag[i] + kt * 64), (void LAS*)(sa + (i * 256 + tid) * 16), 16, 0, 0);
;   };
;   auto stage_b = [&](int kt, int buf) {
;     char* sb = lds + buf * 32768 + 16384;
; #pragma unroll
;     for (int i = 0; i < 4; ++i)
;       __builtin_amdgcn_global_load_lds((const void __attribute__((address_space(1)))*)(bg[i] + kt * 64), (void LAS*)(sb + (i * 256 + tid) * 16), 16, 0, 0);
;   };
;   __syncthreads();
;   stage_a(0, 0); stage_b(0, 0);
;   const int swz = fr >> 1;
; DI bool xcd_tile(int bid, int G, int i, int MT, int NT, int& tm, int& tn) {
;   if ((G & 7) || (MT & 7)) { const int t = bid + i * G; if (t >= MT * NT) return false; tm = t / NT; tn = t % NT; return true; }
;   const int nbx = G >> 3, x = bid & 7, j = bid >> 3, MS = MT >> 3;
;   const int q = j + nbx * i;
;   if (q >= MS * NT) return false;
;   const int full = NT >> 3, wl = NT & 7;
;   int nb = q / (MS * 8), m, ni;
;   if (nb < full) { const int rem = q - nb * MS * 8; m = rem >> 3; ni = rem & 7; }
;   else { const int rem = q - full * MS * 8; nb = full; m = rem / wl; ni = rem % wl; }
;   tm = x * MS + m; tn = nb * 8 + ni;
;   return true;
; }
.LBB0_674:
	v_readlane_b32 s2, v251, 48
	s_mul_i32 s2, s38, s2
	v_readlane_b32 s3, v251, 49
	s_add_i32 s2, s2, s3
	s_cmpk_lt_i32 s2, 0xea
	s_cbranch_scc0 .LBB0_680
	s_cmpk_gt_i32 s2, 0xd7
	s_mov_b64 s[0:1], -1
	s_cbranch_scc0 .LBB0_677
	s_add_i32 s0, s2, 0xffffff28
	s_lshr_b32 s3, s0, 1
	s_mov_b64 s[0:1], 0
.LBB0_677:
	s_mul_hi_i32 s20, s2, 0x38e38e39
	s_lshr_b32 s21, s20, 31
	s_ashr_i32 s27, s20, 4
	s_add_i32 s27, s27, s21
	s_andn2_b64 vcc, exec, s[0:1]
	s_mov_b32 s0, 1
	s_cbranch_vccnz .LBB0_679
	s_mul_i32 s0, s27, 0xffffffb8
	s_add_i32 s0, s0, s2
	s_ashr_i32 s3, s0, 3
	s_mov_b32 s0, 7
.LBB0_679:
	v_readlane_b32 s1, v251, 50
	s_mul_i32 s1, s1, 9
	s_and_b32 s0, s0, s2
	s_add_i32 s26, s3, s1
	s_lshl_b32 s1, s27, 3
	s_or_b32 s27, s0, s1
	s_mov_b64 s[0:1], -1
.LBB0_680:
	s_mov_b64 s[2:3], -1
	s_and_b64 vcc, exec, s[0:1]
	s_cbranch_vccz .LBB0_668
	v_mov_b32_e32 v34, v138
	s_lshl_b32 s3, s26, 8
	v_lshrrev_b32_e32 v35, 4, v34
	v_xor_b32_e32 v1, v35, v34
	v_lshlrev_b32_e32 v1, 4, v1
	s_lshl_b32 s2, s27, 7
	v_and_b32_e32 v110, 0x70, v1
	v_ashrrev_i32_e32 v1, 3, v34
	v_add_u32_e32 v6, s3, v1
	v_add_u32_e32 v10, s2, v1
	v_add_u32_e32 v1, 0x100, v34
	v_readlane_b32 s4, v253, 36
	v_ashrrev_i32_e32 v1, 3, v1
	v_readlane_b32 s8, v253, 40
	v_readlane_b32 s9, v253, 41
	v_ashrrev_i32_e32 v7, 31, v6
	v_add_u32_e32 v14, s3, v1
	v_add_u32_e32 v18, s2, v1
	v_add_u32_e32 v1, 0x200, v34
	v_lshlrev_b32_e32 v92, 4, v34
	v_lshl_add_u64 v[2:3], s[8:9], 0, v[110:111]
	v_lshlrev_b64 v[6:7], 11, v[6:7]
	v_ashrrev_i32_e32 v1, 3, v1
	v_readfirstlane_b32 s0, v92
	v_lshl_add_u64 v[8:9], v[2:3], 0, v[6:7]
	v_add_u32_e32 v22, s3, v1
	v_add_u32_e32 v26, s2, v1
	v_add_u32_e32 v1, 0x300, v34
	s_mov_b32 m0, s0
	v_ashrrev_i32_e32 v15, 31, v14
	v_ashrrev_i32_e32 v1, 3, v1
	s_barrier
	global_load_lds_dwordx4 v[8:9], off
	v_add_u32_e32 v8, 0x1000, v92
	v_lshlrev_b64 v[14:15], 11, v[14:15]
	v_ashrrev_i32_e32 v23, 31, v22
	v_add_u32_e32 v30, s3, v1
	v_readfirstlane_b32 s0, v8
	v_add_u32_e32 v8, 0x2000, v92
	v_lshl_add_u64 v[16:17], v[2:3], 0, v[14:15]
	v_lshlrev_b64 v[22:23], 11, v[22:23]
	v_ashrrev_i32_e32 v31, 31, v30
	s_mov_b32 m0, s0
	v_readfirstlane_b32 s0, v8
	v_add_u32_e32 v8, 0x3000, v92
	v_readlane_b32 s5, v253, 37
	v_readlane_b32 s6, v253, 38
	v_readlane_b32 s7, v253, 39
	v_readlane_b32 s10, v253, 42
	v_readlane_b32 s11, v253, 43
	v_readlane_b32 s12, v253, 44
	v_readlane_b32 s13, v253, 45
	v_readlane_b32 s14, v253, 46
	v_readlane_b32 s15, v253, 47
	v_readlane_b32 s16, v253, 48
	v_readlane_b32 s17, v253, 49
	v_readlane_b32 s18, v253, 50
	v_readlane_b32 s19, v253, 51
	v_lshl_add_u64 v[24:25], v[2:3], 0, v[22:23]
	v_lshlrev_b64 v[30:31], 11, v[30:31]
	global_load_lds_dwordx4 v[16:17], off
	s_mov_b32 m0, s0
	v_readfirstlane_b32 s0, v8
	v_readlane_b32 s4, v253, 54
	v_lshl_add_u64 v[2:3], v[2:3], 0, v[30:31]
	global_load_lds_dwordx4 v[24:25], off
	s_mov_b32 m0, s0
	v_readlane_b32 s5, v253, 55
	v_ashrrev_i32_e32 v11, 31, v10
	global_load_lds_dwordx4 v[2:3], off
	v_add_u32_e32 v2, 0x4000, v92
	v_lshl_add_u64 v[4:5], s[4:5], 0, v[110:111]
	v_lshlrev_b64 v[10:11], 11, v[10:11]
	v_ashrrev_i32_e32 v19, 31, v18
	v_readfirstlane_b32 s0, v2
	v_add_u32_e32 v2, 0x5000, v92
	v_lshl_add_u64 v[12:13], v[4:5], 0, v[10:11]
	v_lshlrev_b64 v[18:19], 11, v[18:19]
	v_ashrrev_i32_e32 v27, 31, v26
	v_add_u32_e32 v32, s2, v1
	s_mov_b32 m0, s0
	v_readfirstlane_b32 s0, v2
	v_add_u32_e32 v2, 0x6000, v92
	v_lshl_add_u64 v[20:21], v[4:5], 0, v[18:19]
	v_lshlrev_b64 v[26:27], 11, v[26:27]
	v_ashrrev_i32_e32 v33, 31, v32
	global_load_lds_dwordx4 v[12:13], off
	s_mov_b32 m0, s0
	v_readfirstlane_b32 s0, v2
	v_add_u32_e32 v2, 0x7000, v92
	v_lshl_add_u64 v[28:29], v[4:5], 0, v[26:27]
	v_lshlrev_b64 v[32:33], 11, v[32:33]
	global_load_lds_dwordx4 v[20:21], off
	s_mov_b32 m0, s0
	v_readfirstlane_b32 s0, v2
	v_lshl_add_u64 v[4:5], v[4:5], 0, v[32:33]
	global_load_lds_dwordx4 v[28:29], off
	s_mov_b32 m0, s0
	v_and_b32_e32 v86, 15, v34
	global_load_lds_dwordx4 v[4:5], off
	v_bfe_u32 v87, v34, 6, 1
	v_ashrrev_i32_e32 v88, 7, v34
	v_bfe_u32 v1, v34, 4, 2
	v_bfe_u32 v2, v34, 1, 3
	v_lshlrev_b32_e32 v3, 7, v86
	v_lshl_or_b32 v89, v88, 13, v3
	v_lshl_or_b32 v91, v87, 13, v3
	v_bitop3_b32 v3, v1, v2, 4 bitop3:0x36
	v_bitop3_b32 v2, v35, v2, 3 bitop3:0x6c
	v_lshlrev_b32_e32 v93, 4, v2
	v_bitop3_b32 v2, v35, 7, v34 bitop3:0x48
	v_lshlrev_b32_e32 v2, 4, v2
	v_readlane_b32 s0, v254, 6
	v_or_b32_e32 v10, v10, v2
	v_readlane_b32 s1, v254, 7
	v_or_b32_e32 v18, v18, v2
	v_or_b32_e32 v26, v26, v2
	v_or_b32_e32 v32, v32, v2
	v_lshl_add_u64 v[66:67], s[0:1], 0, v[10:11]
	v_lshl_add_u64 v[68:69], s[0:1], 0, v[18:19]
	v_lshl_add_u64 v[70:71], s[0:1], 0, v[26:27]
	v_lshl_add_u64 v[72:73], s[0:1], 0, v[32:33]
	v_readlane_b32 s0, v254, 60
	v_or_b32_e32 v6, v6, v2
	v_readlane_b32 s1, v254, 61
; #define LAS __attribute__((address_space(3)))
; template <class Epi>
; DI void gemm_tile(const bf16_t* __restrict__ A, int lda, const bf16_t* __restrict__ Bt, int ldb, int K, int row0, int col0, char* lds, const Epi& epi) {
;     ...
;   f32x4 acc[4][4];
; #pragma unroll
;   for (int m = 0; m < 4; ++m)
; #pragma unroll
;     for (int n = 0; n < 4; ++n) acc[m][n] = (f32x4){0.f, 0.f, 0.f, 0.f};
;   const int KT = K >> 6;
;   auto stage_a = [&](int kt, int buf) {
;     char* sa = lds + buf * 32768;
; #pragma unroll
;     for (int i = 0; i < 4; ++i)
;       __builtin_amdgcn_global_load_lds((const void __attribute__((address_space(1)))*)(ag[i] + kt * 64), (void LAS*)(sa + (i * 256 + tid) * 16), 16, 0, 0);
;   };
;   auto stage_b = [&](int kt, int buf) {
;     char* sb = lds + buf * 32768 + 16384;
; #pragma unroll
;     for (int i = 0; i < 4; ++i)
;       __builtin_amdgcn_global_load_lds((const void __attribute__((address_space(1)))*)(bg[i] + kt * 64), (void LAS*)(sb + (i * 256 + tid) * 16), 16, 0, 0);
;   };
;   __syncthreads();
;   stage_a(0, 0); stage_b(0, 0);
;   const int swz = fr >> 1;
	v_or_b32_e32 v14, v14, v2
	v_or_b32_e32 v22, v22, v2
	v_or_b32_e32 v30, v30, v2
	v_mov_b32_e32 v2, 0
	v_lshlrev_b32_e32 v90, 4, v3
	v_lshl_add_u64 v[74:75], s[0:1], 0, v[6:7]
	v_lshl_add_u64 v[76:77], s[0:1], 0, v[14:15]
	v_lshl_add_u64 v[78:79], s[0:1], 0, v[22:23]
	v_lshl_add_u64 v[80:81], s[0:1], 0, v[30:31]
	s_mov_b64 s[0:1], 0
	s_mov_b32 s26, 0x8000
	v_mov_b32_e32 v3, v2
	v_mov_b32_e32 v4, v2
	v_mov_b32_e32 v5, v2
	v_mov_b32_e32 v6, v2
	v_mov_b32_e32 v7, v2
	v_mov_b32_e32 v8, v2
	v_mov_b32_e32 v9, v2
	v_mov_b32_e32 v10, v2
	v_mov_b32_e32 v11, v2
	v_mov_b32_e32 v12, v2
	v_mov_b32_e32 v13, v2
	v_mov_b32_e32 v14, v2
	v_mov_b32_e32 v15, v2
	v_mov_b32_e32 v16, v2
	v_mov_b32_e32 v17, v2
	v_mov_b32_e32 v18, v2
	v_mov_b32_e32 v19, v2
	v_mov_b32_e32 v20, v2
	v_mov_b32_e32 v21, v2
	v_mov_b32_e32 v22, v2
	v_mov_b32_e32 v23, v2
	v_mov_b32_e32 v24, v2
	v_mov_b32_e32 v25, v2
	v_mov_b32_e32 v26, v2
	v_mov_b32_e32 v27, v2
	v_mov_b32_e32 v28, v2
	v_mov_b32_e32 v29, v2
	v_mov_b32_e32 v30, v2
	v_mov_b32_e32 v31, v2
	v_mov_b32_e32 v32, v2
	v_mov_b32_e32 v33, v2
	v_mov_b32_e32 v34, v2
	v_mov_b32_e32 v35, v2
	v_mov_b32_e32 v36, v2
	v_mov_b32_e32 v37, v2
	v_mov_b32_e32 v38, v2
	v_mov_b32_e32 v39, v2
	v_mov_b32_e32 v40, v2
	v_mov_b32_e32 v41, v2
	v_mov_b32_e32 v42, v2
	v_mov_b32_e32 v43, v2
	v_mov_b32_e32 v44, v2
	v_mov_b32_e32 v45, v2
	v_mov_b32_e32 v46, v2
	v_mov_b32_e32 v47, v2
	v_mov_b32_e32 v48, v2
	v_mov_b32_e32 v49, v2
	v_mov_b32_e32 v50, v2
	v_mov_b32_e32 v51, v2
	v_mov_b32_e32 v52, v2
	v_mov_b32_e32 v53, v2
	v_mov_b32_e32 v54, v2
	v_mov_b32_e32 v55, v2
	v_mov_b32_e32 v56, v2
	v_mov_b32_e32 v57, v2
	v_mov_b32_e32 v58, v2
	v_mov_b32_e32 v59, v2
	v_mov_b32_e32 v60, v2
	v_mov_b32_e32 v61, v2
	v_mov_b32_e32 v62, v2
	v_mov_b32_e32 v63, v2
	v_mov_b32_e32 v64, v2
	v_mov_b32_e32 v65, v2
	v_readlane_b32 s6, v253, 56
	v_readlane_b32 s7, v253, 57
	v_readlane_b32 s8, v253, 58
	v_readlane_b32 s9, v253, 59
	v_readlane_b32 s10, v253, 60
	v_readlane_b32 s11, v253, 61
	v_readlane_b32 s12, v253, 62
	v_readlane_b32 s13, v253, 63
	v_readlane_b32 s14, v254, 0
	v_readlane_b32 s15, v254, 1
	v_readlane_b32 s16, v254, 2
	v_readlane_b32 s17, v254, 3
	v_readlane_b32 s18, v254, 4
	v_readlane_b32 s19, v254, 5
	v_mov_b32_e32 v162, 0
	v_mov_b32_e32 v163, 0
	v_mov_b32_e32 v164, 0
	v_mov_b32_e32 v165, 0
	v_mov_b32_e32 v166, 0
	v_mov_b32_e32 v167, 0
	v_mov_b32_e32 v168, 0
	v_mov_b32_e32 v169, 0
	v_mov_b32_e32 v170, 0
	v_mov_b32_e32 v171, 0
	v_mov_b32_e32 v172, 0
	v_mov_b32_e32 v173, 0
	v_mov_b32_e32 v174, 0
	v_mov_b32_e32 v175, 0
	v_mov_b32_e32 v176, 0
	v_mov_b32_e32 v177, 0
	v_mov_b32_e32 v178, 0
	v_mov_b32_e32 v179, 0
	v_mov_b32_e32 v180, 0
	v_mov_b32_e32 v181, 0
	v_mov_b32_e32 v182, 0
	v_mov_b32_e32 v183, 0
	v_mov_b32_e32 v184, 0
	v_mov_b32_e32 v185, 0
	v_mov_b32_e32 v186, 0
	v_mov_b32_e32 v187, 0
	v_mov_b32_e32 v188, 0
	v_mov_b32_e32 v189, 0
	v_mov_b32_e32 v190, 0
	v_mov_b32_e32 v191, 0
	v_mov_b32_e32 v192, 0
	v_mov_b32_e32 v193, 0
	v_mov_b32_e32 v194, 0
	v_mov_b32_e32 v195, 0
	v_mov_b32_e32 v196, 0
	v_mov_b32_e32 v197, 0
	v_mov_b32_e32 v198, 0
	v_mov_b32_e32 v199, 0
	v_mov_b32_e32 v200, 0
	v_mov_b32_e32 v201, 0
	v_mov_b32_e32 v202, 0
	v_mov_b32_e32 v203, 0
	v_mov_b32_e32 v204, 0
	v_mov_b32_e32 v205, 0
	v_mov_b32_e32 v206, 0
	v_mov_b32_e32 v207, 0
	v_mov_b32_e32 v208, 0
	v_mov_b32_e32 v209, 0
	v_mov_b32_e32 v210, 0
	v_mov_b32_e32 v211, 0
	v_mov_b32_e32 v212, 0
	v_mov_b32_e32 v213, 0
	v_mov_b32_e32 v214, 0
	v_mov_b32_e32 v215, 0
	v_mov_b32_e32 v216, 0
	v_mov_b32_e32 v217, 0
	v_mov_b32_e32 v218, 0
	v_mov_b32_e32 v219, 0
	v_mov_b32_e32 v220, 0
	v_mov_b32_e32 v221, 0
	v_mov_b32_e32 v222, 0
	v_mov_b32_e32 v223, 0
	v_mov_b32_e32 v224, 0
	v_mov_b32_e32 v225, 0
	v_readfirstlane_b32 s21, v92
	v_add_u32_e32 v242, v89, v93
	v_add_u32_e32 v243, v91, v93
	v_add_u32_e32 v244, v89, v90
	v_add_u32_e32 v245, v91, v90
	s_mov_b32 s0, 0x3ff80
	s_mov_b32 s1, 0
	s_add_i32 m0, s21, 0x8000
	v_lshl_add_u64 v[82:83], v[74:75], 0, s[0:1]
	global_load_lds_dwordx4 v[82:83], off
	s_add_i32 m0, m0, 0x1000
	v_lshl_add_u64 v[82:83], v[76:77], 0, s[0:1]
	global_load_lds_dwordx4 v[82:83], off
	s_add_i32 m0, m0, 0x1000
	v_lshl_add_u64 v[82:83], v[78:79], 0, s[0:1]
	global_load_lds_dwordx4 v[82:83], off
	s_add_i32 m0, m0, 0x1000
	v_lshl_add_u64 v[82:83], v[80:81], 0, s[0:1]
	global_load_lds_dwordx4 v[82:83], off
	s_mov_b64 s[0:1], 0
	s_add_i32 m0, s21, 0xc000
	v_lshl_add_u64 v[82:83], v[66:67], 0, s[0:1]
	global_load_lds_dwordx4 v[82:83], off
	s_add_i32 m0, m0, 0x1000
	v_lshl_add_u64 v[82:83], v[68:69], 0, s[0:1]
	global_load_lds_dwordx4 v[82:83], off
	s_add_i32 m0, m0, 0x1000
	v_lshl_add_u64 v[82:83], v[70:71], 0, s[0:1]
	global_load_lds_dwordx4 v[82:83], off
	s_add_i32 m0, m0, 0x1000
	v_lshl_add_u64 v[82:83], v[72:73], 0, s[0:1]
	global_load_lds_dwordx4 v[82:83], off

; template <class Epi>
; DI void gemm_tile(const bf16_t* __restrict__ A, int lda, const bf16_t* __restrict__ Bt, int ldb, int K, int row0, int col0, char* lds, const Epi& epi) {
;     ...
;   for (int kt = 0; kt < KT; ++kt) {
;     asm volatile("s_waitcnt vmcnt(0)" ::: "memory");
;     __syncthreads();
;     const char* sa = lds + (kt & 1) * 32768 + (wr * 64 + fr) * 128;
;     const char* sb = lds + (kt & 1) * 32768 + 16384 + (wc * 64 + fr) * 128;
; #pragma unroll
;     for (int kk = 0; kk < 2; ++kk) {
;       if (kt + 1 < KT) { if (kk == 0) stage_a(kt + 1, (kt + 1) & 1); else stage_b(kt + 1, (kt + 1) & 1); }
;       bf16x8 a[4], b[4];
;       const int co = ((kk * 4 + fq) ^ swz) * 16;
; #pragma unroll
;       for (int m = 0; m < 4; ++m) a[m] = *(const bf16x8*)(sa + m * 2048 + co);
; #pragma unroll
;       for (int n = 0; n < 4; ++n) b[n] = *(const bf16x8*)(sb + n * 2048 + co);
; #pragma unroll
;       for (int m = 0; m < 4; ++m)
; #pragma unroll
;         for (int n = 0; n < 4; ++n) acc[m][n] = __builtin_amdgcn_mfma_f32_16x16x32_bf16(b[n], a[m], acc[m][n], 0, 0, 0);
;   DI void operator()(const f32x4 (&acc)[4][4], int r0, int c0, int fr, int fq) const {
;     bf16_t* base; int ld, cb;
;     if (c0 < LDPA) { base = PA; ld = LDPA; cb = c0; } else { base = PBC; ld = LDPBC; cb = c0 - LDPA; }
;     if (c0 >= LDPA && cb < 1024) {
;       float* dst = SSQ + (cb < 768 ? 0 : T_TOK);
; #pragma unroll
;       for (int m = 0; m < 4; ++m) {
;         float ss = 0.f;
; #pragma unroll
;         for (int n = 0; n < 4; ++n)
; #pragma unroll
;           for (int j = 0; j < 4; ++j) ss += acc[m][n][j] * acc[m][n][j];
;         ss += __shfl_xor(ss, 16); ss += __shfl_xor(ss, 32);
;         if (fq == 0) atomicAdd(dst + r0 + m * 16 + fr, ss);
;       }
;     }
.Lp2_noa:
	v_mfma_f32_16x16x32_bf16 v[62:65], v[116:119], v[94:97], v[62:65]
	v_mfma_f32_16x16x32_bf16 v[58:61], v[120:123], v[94:97], v[58:61]
	v_mfma_f32_16x16x32_bf16 v[54:57], v[124:127], v[94:97], v[54:57]
	v_mfma_f32_16x16x32_bf16 v[50:53], v[128:131], v[94:97], v[50:53]
	v_mfma_f32_16x16x32_bf16 v[46:49], v[116:119], v[98:101], v[46:49]
	v_mfma_f32_16x16x32_bf16 v[42:45], v[120:123], v[98:101], v[42:45]
	v_mfma_f32_16x16x32_bf16 v[38:41], v[124:127], v[98:101], v[38:41]
	v_mfma_f32_16x16x32_bf16 v[34:37], v[128:131], v[98:101], v[34:37]
	v_mfma_f32_16x16x32_bf16 v[30:33], v[116:119], v[102:105], v[30:33]
	v_mfma_f32_16x16x32_bf16 v[26:29], v[120:123], v[102:105], v[26:29]
	v_mfma_f32_16x16x32_bf16 v[22:25], v[124:127], v[102:105], v[22:25]
	v_mfma_f32_16x16x32_bf16 v[18:21], v[128:131], v[102:105], v[18:21]
	v_mfma_f32_16x16x32_bf16 v[14:17], v[116:119], v[106:109], v[14:17]
	v_mfma_f32_16x16x32_bf16 v[10:13], v[120:123], v[106:109], v[10:13]
	v_mfma_f32_16x16x32_bf16 v[6:9], v[124:127], v[106:109], v[6:9]
	v_mfma_f32_16x16x32_bf16 v[2:5], v[128:131], v[106:109], v[2:5]
	v_mfma_f32_16x16x32_bf16 v[222:225], v[116:119], v[226:229], v[222:225]
	v_mfma_f32_16x16x32_bf16 v[218:221], v[120:123], v[226:229], v[218:221]
	v_mfma_f32_16x16x32_bf16 v[214:217], v[124:127], v[226:229], v[214:217]
	v_mfma_f32_16x16x32_bf16 v[210:213], v[128:131], v[226:229], v[210:213]
	v_mfma_f32_16x16x32_bf16 v[206:209], v[116:119], v[230:233], v[206:209]
	v_mfma_f32_16x16x32_bf16 v[202:205], v[120:123], v[230:233], v[202:205]
	v_mfma_f32_16x16x32_bf16 v[198:201], v[124:127], v[230:233], v[198:201]
	v_mfma_f32_16x16x32_bf16 v[194:197], v[128:131], v[230:233], v[194:197]
	v_mfma_f32_16x16x32_bf16 v[190:193], v[116:119], v[234:237], v[190:193]
	v_mfma_f32_16x16x32_bf16 v[186:189], v[120:123], v[234:237], v[186:189]
	v_mfma_f32_16x16x32_bf16 v[182:185], v[124:127], v[234:237], v[182:185]
	v_mfma_f32_16x16x32_bf16 v[178:181], v[128:131], v[234:237], v[178:181]
	v_mfma_f32_16x16x32_bf16 v[174:177], v[116:119], v[238:241], v[174:177]
	v_mfma_f32_16x16x32_bf16 v[170:173], v[120:123], v[238:241], v[170:173]
	v_mfma_f32_16x16x32_bf16 v[166:169], v[124:127], v[238:241], v[166:169]
	v_mfma_f32_16x16x32_bf16 v[162:165], v[128:131], v[238:241], v[162:165]
	s_add_u32 s0, s0, 0x80
	s_cmpk_lg_i32 s0, 0x800
	s_cbranch_scc1 .LBB0_682
	v_lshl_or_b32 v84, v87, 6, s2
	v_readlane_b32 s4, v253, 28
	v_readlane_b32 s5, v253, 29
	v_readlane_b32 s6, v253, 30
	v_readlane_b32 s7, v253, 31
	v_readfirstlane_b32 s8, v84
	v_xor_b32_e32 v94, 16, v147
	v_lshlrev_b32_e32 v94, 2, v94
	v_xor_b32_e32 v95, 32, v147
	v_lshlrev_b32_e32 v95, 2, v95
	s_cmpk_lt_i32 s8, 0x580
	s_cselect_b32 s12, s4, s6
	s_cselect_b32 s13, s5, s7
	s_movk_i32 s17, 0xf00
	s_cselect_b32 s17, 0xb00, s17
	s_cselect_b32 s9, 0, 0x580
	s_cselect_b32 s14, 0, 1
	s_sub_i32 s10, s8, s9
	s_cmpk_lt_i32 s10, 0x400
	s_cselect_b32 s15, 1, 0
	s_and_b32 s14, s14, s15
	s_cmpk_lt_i32 s10, 0x300
	s_cselect_b32 s15, 0, 0x12000
	s_lshl_b32 s16, s10, 1
	v_lshlrev_b32_e32 v85, 3, v1
	v_add_u32_e32 v85, s16, v85
	v_or_b32_e32 v83, s3, v86
	v_lshl_add_u32 v83, v88, 6, v83
	s_cmp_eq_u32 s14, 0
	s_cbranch_scc1 .Lp2_nossq0
	v_lshlrev_b32_e32 v81, 2, v83
	v_add_u32_e32 v81, s15, v81
	v_cmp_eq_u32_e32 vcc, 0, v1
	v_mul_f32_e32 v80, v62, v62
	v_fmac_f32_e32 v80, v63, v63
	v_fmac_f32_e32 v80, v64, v64
	v_fmac_f32_e32 v80, v65, v65
	v_fmac_f32_e32 v80, v58, v58
	v_fmac_f32_e32 v80, v59, v59
	v_fmac_f32_e32 v80, v60, v60
	v_fmac_f32_e32 v80, v61, v61
	v_fmac_f32_e32 v80, v54, v54
	v_fmac_f32_e32 v80, v55, v55
	v_fmac_f32_e32 v80, v56, v56
	v_fmac_f32_e32 v80, v57, v57
	v_fmac_f32_e32 v80, v50, v50
	v_fmac_f32_e32 v80, v51, v51
	v_fmac_f32_e32 v80, v52, v52
	v_fmac_f32_e32 v80, v53, v53
	s_nop 0
	ds_bpermute_b32 v96, v94, v80
	s_waitcnt lgkmcnt(0)
	v_add_f32_e32 v80, v80, v96
	s_nop 0
	ds_bpermute_b32 v96, v95, v80
	s_waitcnt lgkmcnt(0)
	v_add_f32_e32 v80, v80, v96
	s_and_saveexec_b64 s[18:19], vcc
	global_atomic_add_f32 v81, v80, s[60:61]
	s_or_b64 exec, exec, s[18:19]
	v_mul_f32_e32 v80, v46, v46
	v_fmac_f32_e32 v80, v47, v47
	v_fmac_f32_e32 v80, v48, v48
	v_fmac_f32_e32 v80, v49, v49
	v_fmac_f32_e32 v80, v42, v42
	v_fmac_f32_e32 v80, v43, v43
	v_fmac_f32_e32 v80, v44, v44
	v_fmac_f32_e32 v80, v45, v45
	v_fmac_f32_e32 v80, v38, v38
	v_fmac_f32_e32 v80, v39, v39
	v_fmac_f32_e32 v80, v40, v40
	v_fmac_f32_e32 v80, v41, v41
	v_fmac_f32_e32 v80, v34, v34
	v_fmac_f32_e32 v80, v35, v35
	v_fmac_f32_e32 v80, v36, v36
	v_fmac_f32_e32 v80, v37, v37
	s_nop 0
	ds_bpermute_b32 v96, v94, v80
	s_waitcnt lgkmcnt(0)
	v_add_f32_e32 v80, v80, v96
	s_nop 0
	ds_bpermute_b32 v96, v95, v80
	s_waitcnt lgkmcnt(0)
	v_add_f32_e32 v80, v80, v96
	s_and_saveexec_b64 s[18:19], vcc
	global_atomic_add_f32 v81, v80, s[60:61] offset:64
	s_or_b64 exec, exec, s[18:19]
	v_mul_f32_e32 v80, v30, v30
	v_fmac_f32_e32 v80, v31, v31
	v_fmac_f32_e32 v80, v32, v32
	v_fmac_f32_e32 v80, v33, v33
	v_fmac_f32_e32 v80, v26, v26
	v_fmac_f32_e32 v80, v27, v27
	v_fmac_f32_e32 v80, v28, v28
	v_fmac_f32_e32 v80, v29, v29
	v_fmac_f32_e32 v80, v22, v22
	v_fmac_f32_e32 v80, v23, v23
	v_fmac_f32_e32 v80, v24, v24
	v_fmac_f32_e32 v80, v25, v25
	v_fmac_f32_e32 v80, v18, v18
	v_fmac_f32_e32 v80, v19, v19
	v_fmac_f32_e32 v80, v20, v20
	v_fmac_f32_e32 v80, v21, v21
	s_nop 0
	ds_bpermute_b32 v96, v94, v80
	s_waitcnt lgkmcnt(0)
	v_add_f32_e32 v80, v80, v96
	s_nop 0
	ds_bpermute_b32 v96, v95, v80
	s_waitcnt lgkmcnt(0)
	v_add_f32_e32 v80, v80, v96
	s_and_saveexec_b64 s[18:19], vcc
	global_atomic_add_f32 v81, v80, s[60:61] offset:128
	s_or_b64 exec, exec, s[18:19]
	v_mul_f32_e32 v80, v14, v14
	v_fmac_f32_e32 v80, v15, v15
	v_fmac_f32_e32 v80, v16, v16
	v_fmac_f32_e32 v80, v17, v17
	v_fmac_f32_e32 v80, v10, v10
	v_fmac_f32_e32 v80, v11, v11
	v_fmac_f32_e32 v80, v12, v12
	v_fmac_f32_e32 v80, v13, v13
	v_fmac_f32_e32 v80, v6, v6
	v_fmac_f32_e32 v80, v7, v7
	v_fmac_f32_e32 v80, v8, v8
	v_fmac_f32_e32 v80, v9, v9
	v_fmac_f32_e32 v80, v2, v2
	v_fmac_f32_e32 v80, v3, v3
	v_fmac_f32_e32 v80, v4, v4
	v_fmac_f32_e32 v80, v5, v5
	s_nop 0
	ds_bpermute_b32 v96, v94, v80
	s_waitcnt lgkmcnt(0)
	v_add_f32_e32 v80, v80, v96
	s_nop 0
	ds_bpermute_b32 v96, v95, v80
	s_waitcnt lgkmcnt(0)
	v_add_f32_e32 v80, v80, v96
	s_and_saveexec_b64 s[18:19], vcc
	global_atomic_add_f32 v81, v80, s[60:61] offset:192
	s_or_b64 exec, exec, s[18:19]
; DI unsigned pk_bf16(float lo, float hi) { f32x2 v = {lo, hi}; bf16v2 b = __builtin_convertvector(v, bf16v2); return __builtin_bit_cast(unsigned, b); }
;   DI void operator()(const f32x4 (&acc)[4][4], int r0, int c0, int fr, int fq) const {
;     ...
; #pragma unroll
;     for (int m = 0; m < 4; ++m)
; #pragma unroll
;       for (int n = 0; n < 4; ++n) {
;         u32x2 v = {pk_bf16(acc[m][n][0], acc[m][n][1]), pk_bf16(acc[m][n][2], acc[m][n][3])};
;         *(u32x2*)(base + (size_t)(r0 + m * 16 + fr) * ld + cb + n * 16 + fq * 4) = v;
;       }
.Lp2_nossq0:
	v_mul_lo_u32 v82, v83, s17
	v_add_u32_e32 v82, v82, v85
	v_cvt_pk_bf16_f32 v98, v62, v63
	v_cvt_pk_bf16_f32 v99, v64, v65
	global_store_dwordx2 v82, v[98:99], s[12:13]
	v_cvt_pk_bf16_f32 v100, v58, v59
	v_cvt_pk_bf16_f32 v101, v60, v61
	global_store_dwordx2 v82, v[100:101], s[12:13] offset:32
	v_cvt_pk_bf16_f32 v98, v54, v55
	v_cvt_pk_bf16_f32 v99, v56, v57
	global_store_dwordx2 v82, v[98:99], s[12:13] offset:64
	v_cvt_pk_bf16_f32 v100, v50, v51
	v_cvt_pk_bf16_f32 v101, v52, v53
	global_store_dwordx2 v82, v[100:101], s[12:13] offset:96
	v_add_u32_e32 v83, 16, v83
	v_mul_lo_u32 v82, v83, s17
	v_add_u32_e32 v82, v82, v85
	v_cvt_pk_bf16_f32 v98, v46, v47
	v_cvt_pk_bf16_f32 v99, v48, v49
	global_store_dwordx2 v82, v[98:99], s[12:13]
	v_cvt_pk_bf16_f32 v100, v42, v43
	v_cvt_pk_bf16_f32 v101, v44, v45
	global_store_dwordx2 v82, v[100:101], s[12:13] offset:32
	v_cvt_pk_bf16_f32 v98, v38, v39
	v_cvt_pk_bf16_f32 v99, v40, v41
	global_store_dwordx2 v82, v[98:99], s[12:13] offset:64
	v_cvt_pk_bf16_f32 v100, v34, v35
	v_cvt_pk_bf16_f32 v101, v36, v37
	global_store_dwordx2 v82, v[100:101], s[12:13] offset:96
	v_add_u32_e32 v83, 16, v83
	v_mul_lo_u32 v82, v83, s17
	v_add_u32_e32 v82, v82, v85
	v_cvt_pk_bf16_f32 v98, v30, v31
	v_cvt_pk_bf16_f32 v99, v32, v33
	global_store_dwordx2 v82, v[98:99], s[12:13]
	v_cvt_pk_bf16_f32 v100, v26, v27
	v_cvt_pk_bf16_f32 v101, v28, v29
	global_store_dwordx2 v82, v[100:101], s[12:13] offset:32
	v_cvt_pk_bf16_f32 v98, v22, v23
	v_cvt_pk_bf16_f32 v99, v24, v25
	global_store_dwordx2 v82, v[98:99], s[12:13] offset:64
	v_cvt_pk_bf16_f32 v100, v18, v19
	v_cvt_pk_bf16_f32 v101, v20, v21
	global_store_dwordx2 v82, v[100:101], s[12:13] offset:96
	v_add_u32_e32 v83, 16, v83
	v_mul_lo_u32 v82, v83, s17
	v_add_u32_e32 v82, v82, v85
	v_cvt_pk_bf16_f32 v98, v14, v15
	v_cvt_pk_bf16_f32 v99, v16, v17
	global_store_dwordx2 v82, v[98:99], s[12:13]
	v_cvt_pk_bf16_f32 v100, v10, v11
	v_cvt_pk_bf16_f32 v101, v12, v13
	global_store_dwordx2 v82, v[100:101], s[12:13] offset:32
	v_cvt_pk_bf16_f32 v98, v6, v7
	v_cvt_pk_bf16_f32 v99, v8, v9
	global_store_dwordx2 v82, v[98:99], s[12:13] offset:64
	v_cvt_pk_bf16_f32 v100, v2, v3
	v_cvt_pk_bf16_f32 v101, v4, v5
	global_store_dwordx2 v82, v[100:101], s[12:13] offset:96
	v_mov_b32_e32 v2, v162
	v_mov_b32_e32 v3, v163
	v_mov_b32_e32 v4, v164
	v_mov_b32_e32 v5, v165
	v_mov_b32_e32 v6, v166
	v_mov_b32_e32 v7, v167
	v_mov_b32_e32 v8, v168
	v_mov_b32_e32 v9, v169
	v_mov_b32_e32 v10, v170
	v_mov_b32_e32 v11, v171
	v_mov_b32_e32 v12, v172
	v_mov_b32_e32 v13, v173
	v_mov_b32_e32 v14, v174
	v_mov_b32_e32 v15, v175
	v_mov_b32_e32 v16, v176
	v_mov_b32_e32 v17, v177
	v_mov_b32_e32 v18, v178
	v_mov_b32_e32 v19, v179
	v_mov_b32_e32 v20, v180
	v_mov_b32_e32 v21, v181
	v_mov_b32_e32 v22, v182
	v_mov_b32_e32 v23, v183
	v_mov_b32_e32 v24, v184
	v_mov_b32_e32 v25, v185
	v_mov_b32_e32 v26, v186
	v_mov_b32_e32 v27, v187
	v_mov_b32_e32 v28, v188
	v_mov_b32_e32 v29, v189
	v_mov_b32_e32 v30, v190
	v_mov_b32_e32 v31, v191
	v_mov_b32_e32 v32, v192
	v_mov_b32_e32 v33, v193
	v_mov_b32_e32 v34, v194
	v_mov_b32_e32 v35, v195
	v_mov_b32_e32 v36, v196
	v_mov_b32_e32 v37, v197
	v_mov_b32_e32 v38, v198
	v_mov_b32_e32 v39, v199
	v_mov_b32_e32 v40, v200
	v_mov_b32_e32 v41, v201
	v_mov_b32_e32 v42, v202
	v_mov_b32_e32 v43, v203
	v_mov_b32_e32 v44, v204
	v_mov_b32_e32 v45, v205
	v_mov_b32_e32 v46, v206
	v_mov_b32_e32 v47, v207
	v_mov_b32_e32 v48, v208
	v_mov_b32_e32 v49, v209
	v_mov_b32_e32 v50, v210
	v_mov_b32_e32 v51, v211
	v_mov_b32_e32 v52, v212
	v_mov_b32_e32 v53, v213
	v_mov_b32_e32 v54, v214
	v_mov_b32_e32 v55, v215
	v_mov_b32_e32 v56, v216
	v_mov_b32_e32 v57, v217
	v_mov_b32_e32 v58, v218
	v_mov_b32_e32 v59, v219
	v_mov_b32_e32 v60, v220
	v_mov_b32_e32 v61, v221
	v_mov_b32_e32 v62, v222
	v_mov_b32_e32 v63, v223
	v_mov_b32_e32 v64, v224
	v_mov_b32_e32 v65, v225
	s_add_i32 s11, s3, 0x80
	v_or_b32_e32 v83, s11, v86
	v_lshl_add_u32 v83, v88, 6, v83
	s_cmp_eq_u32 s14, 0
	s_cbranch_scc1 .Lp2_nossq1
; DI unsigned pk_bf16(float lo, float hi) { f32x2 v = {lo, hi}; bf16v2 b = __builtin_convertvector(v, bf16v2); return __builtin_bit_cast(unsigned, b); }
;   DI void operator()(const f32x4 (&acc)[4][4], int r0, int c0, int fr, int fq) const {
;     ...
;     if (c0 >= LDPA && cb < 1024) {
;       float* dst = SSQ + (cb < 768 ? 0 : T_TOK);
; #pragma unroll
;       for (int m = 0; m < 4; ++m) {
;         float ss = 0.f;
; #pragma unroll
;         for (int n = 0; n < 4; ++n)
; #pragma unroll
;           for (int j = 0; j < 4; ++j) ss += acc[m][n][j] * acc[m][n][j];
;         ss += __shfl_xor(ss, 16); ss += __shfl_xor(ss, 32);
;         if (fq == 0) atomicAdd(dst + r0 + m * 16 + fr, ss);
;       }
;     }
; #pragma unroll
;     for (int m = 0; m < 4; ++m)
; #pragma unroll
;       for (int n = 0; n < 4; ++n) {
;         u32x2 v = {pk_bf16(acc[m][n][0], acc[m][n][1]), pk_bf16(acc[m][n][2], acc[m][n][3])};
;         *(u32x2*)(base + (size_t)(r0 + m * 16 + fr) * ld + cb + n * 16 + fq * 4) = v;
;       }
	v_lshlrev_b32_e32 v81, 2, v83
	v_add_u32_e32 v81, s15, v81
	v_cmp_eq_u32_e32 vcc, 0, v1
	v_mul_f32_e32 v80, v62, v62
	v_fmac_f32_e32 v80, v63, v63
	v_fmac_f32_e32 v80, v64, v64
	v_fmac_f32_e32 v80, v65, v65
	v_fmac_f32_e32 v80, v58, v58
	v_fmac_f32_e32 v80, v59, v59
	v_fmac_f32_e32 v80, v60, v60
	v_fmac_f32_e32 v80, v61, v61
	v_fmac_f32_e32 v80, v54, v54
	v_fmac_f32_e32 v80, v55, v55
	v_fmac_f32_e32 v80, v56, v56
	v_fmac_f32_e32 v80, v57, v57
	v_fmac_f32_e32 v80, v50, v50
	v_fmac_f32_e32 v80, v51, v51
	v_fmac_f32_e32 v80, v52, v52
	v_fmac_f32_e32 v80, v53, v53
	s_nop 0
	ds_bpermute_b32 v96, v94, v80
	s_waitcnt lgkmcnt(0)
	v_add_f32_e32 v80, v80, v96
	s_nop 0
	ds_bpermute_b32 v96, v95, v80
	s_waitcnt lgkmcnt(0)
	v_add_f32_e32 v80, v80, v96
	s_and_saveexec_b64 s[18:19], vcc
	global_atomic_add_f32 v81, v80, s[60:61]
	s_or_b64 exec, exec, s[18:19]
	v_mul_f32_e32 v80, v46, v46
	v_fmac_f32_e32 v80, v47, v47
	v_fmac_f32_e32 v80, v48, v48
	v_fmac_f32_e32 v80, v49, v49
	v_fmac_f32_e32 v80, v42, v42
	v_fmac_f32_e32 v80, v43, v43
	v_fmac_f32_e32 v80, v44, v44
	v_fmac_f32_e32 v80, v45, v45
	v_fmac_f32_e32 v80, v38, v38
	v_fmac_f32_e32 v80, v39, v39
	v_fmac_f32_e32 v80, v40, v40
	v_fmac_f32_e32 v80, v41, v41
	v_fmac_f32_e32 v80, v34, v34
	v_fmac_f32_e32 v80, v35, v35
	v_fmac_f32_e32 v80, v36, v36
	v_fmac_f32_e32 v80, v37, v37
	s_nop 0
	ds_bpermute_b32 v96, v94, v80
	s_waitcnt lgkmcnt(0)
	v_add_f32_e32 v80, v80, v96
	s_nop 0
	ds_bpermute_b32 v96, v95, v80
	s_waitcnt lgkmcnt(0)
	v_add_f32_e32 v80, v80, v96
	s_and_saveexec_b64 s[18:19], vcc
	global_atomic_add_f32 v81, v80, s[60:61] offset:64
	s_or_b64 exec, exec, s[18:19]
	v_mul_f32_e32 v80, v30, v30
	v_fmac_f32_e32 v80, v31, v31
	v_fmac_f32_e32 v80, v32, v32
	v_fmac_f32_e32 v80, v33, v33
	v_fmac_f32_e32 v80, v26, v26
	v_fmac_f32_e32 v80, v27, v27
	v_fmac_f32_e32 v80, v28, v28
	v_fmac_f32_e32 v80, v29, v29
	v_fmac_f32_e32 v80, v22, v22
	v_fmac_f32_e32 v80, v23, v23
	v_fmac_f32_e32 v80, v24, v24
	v_fmac_f32_e32 v80, v25, v25
	v_fmac_f32_e32 v80, v18, v18
	v_fmac_f32_e32 v80, v19, v19
	v_fmac_f32_e32 v80, v20, v20
	v_fmac_f32_e32 v80, v21, v21
	s_nop 0
	ds_bpermute_b32 v96, v94, v80
	s_waitcnt lgkmcnt(0)
	v_add_f32_e32 v80, v80, v96
	s_nop 0
	ds_bpermute_b32 v96, v95, v80
	s_waitcnt lgkmcnt(0)
	v_add_f32_e32 v80, v80, v96
	s_and_saveexec_b64 s[18:19], vcc
	global_atomic_add_f32 v81, v80, s[60:61] offset:128
	s_or_b64 exec, exec, s[18:19]
	v_mul_f32_e32 v80, v14, v14
	v_fmac_f32_e32 v80, v15, v15
	v_fmac_f32_e32 v80, v16, v16
	v_fmac_f32_e32 v80, v17, v17
	v_fmac_f32_e32 v80, v10, v10
	v_fmac_f32_e32 v80, v11, v11
	v_fmac_f32_e32 v80, v12, v12
	v_fmac_f32_e32 v80, v13, v13
	v_fmac_f32_e32 v80, v6, v6
	v_fmac_f32_e32 v80, v7, v7
	v_fmac_f32_e32 v80, v8, v8
	v_fmac_f32_e32 v80, v9, v9
	v_fmac_f32_e32 v80, v2, v2
	v_fmac_f32_e32 v80, v3, v3
	v_fmac_f32_e32 v80, v4, v4
	v_fmac_f32_e32 v80, v5, v5
	s_nop 0
	ds_bpermute_b32 v96, v94, v80
	s_waitcnt lgkmcnt(0)
	v_add_f32_e32 v80, v80, v96
	s_nop 0
	ds_bpermute_b32 v96, v95, v80
	s_waitcnt lgkmcnt(0)
	v_add_f32_e32 v80, v80, v96
	s_and_saveexec_b64 s[18:19], vcc
	global_atomic_add_f32 v81, v80, s[60:61] offset:192
	s_or_b64 exec, exec, s[18:19]
.Lp2_nossq1:
	v_mul_lo_u32 v82, v83, s17
	v_add_u32_e32 v82, v82, v85
	v_cvt_pk_bf16_f32 v98, v62, v63
	v_cvt_pk_bf16_f32 v99, v64, v65
	global_store_dwordx2 v82, v[98:99], s[12:13]
	v_cvt_pk_bf16_f32 v100, v58, v59
	v_cvt_pk_bf16_f32 v101, v60, v61
	global_store_dwordx2 v82, v[100:101], s[12:13] offset:32
	v_cvt_pk_bf16_f32 v98, v54, v55
	v_cvt_pk_bf16_f32 v99, v56, v57
	global_store_dwordx2 v82, v[98:99], s[12:13] offset:64
	v_cvt_pk_bf16_f32 v100, v50, v51
	v_cvt_pk_bf16_f32 v101, v52, v53
	global_store_dwordx2 v82, v[100:101], s[12:13] offset:96
	v_add_u32_e32 v83, 16, v83
	v_mul_lo_u32 v82, v83, s17
	v_add_u32_e32 v82, v82, v85
	v_cvt_pk_bf16_f32 v98, v46, v47
	v_cvt_pk_bf16_f32 v99, v48, v49
	global_store_dwordx2 v82, v[98:99], s[12:13]
	v_cvt_pk_bf16_f32 v100, v42, v43
	v_cvt_pk_bf16_f32 v101, v44, v45
	global_store_dwordx2 v82, v[100:101], s[12:13] offset:32
	v_cvt_pk_bf16_f32 v98, v38, v39
	v_cvt_pk_bf16_f32 v99, v40, v41
	global_store_dwordx2 v82, v[98:99], s[12:13] offset:64
	v_cvt_pk_bf16_f32 v100, v34, v35
	v_cvt_pk_bf16_f32 v101, v36, v37
	global_store_dwordx2 v82, v[100:101], s[12:13] offset:96
	v_add_u32_e32 v83, 16, v83
	v_mul_lo_u32 v82, v83, s17
	v_add_u32_e32 v82, v82, v85
	v_cvt_pk_bf16_f32 v98, v30, v31
	v_cvt_pk_bf16_f32 v99, v32, v33
	global_store_dwordx2 v82, v[98:99], s[12:13]
	v_cvt_pk_bf16_f32 v100, v26, v27
	v_cvt_pk_bf16_f32 v101, v28, v29
	global_store_dwordx2 v82, v[100:101], s[12:13] offset:32
	v_cvt_pk_bf16_f32 v98, v22, v23
	v_cvt_pk_bf16_f32 v99, v24, v25
	global_store_dwordx2 v82, v[98:99], s[12:13] offset:64
	v_cvt_pk_bf16_f32 v100, v18, v19
	v_cvt_pk_bf16_f32 v101, v20, v21
	global_store_dwordx2 v82, v[100:101], s[12:13] offset:96
	v_add_u32_e32 v83, 16, v83
	v_mul_lo_u32 v82, v83, s17
	v_add_u32_e32 v82, v82, v85
	v_cvt_pk_bf16_f32 v98, v14, v15
	v_cvt_pk_bf16_f32 v99, v16, v17
	global_store_dwordx2 v82, v[98:99], s[12:13]
	v_cvt_pk_bf16_f32 v100, v10, v11
	v_cvt_pk_bf16_f32 v101, v12, v13
	global_store_dwordx2 v82, v[100:101], s[12:13] offset:32
	v_cvt_pk_bf16_f32 v98, v6, v7
	v_cvt_pk_bf16_f32 v99, v8, v9
	global_store_dwordx2 v82, v[98:99], s[12:13] offset:64
	v_cvt_pk_bf16_f32 v100, v2, v3
	v_cvt_pk_bf16_f32 v101, v4, v5
	global_store_dwordx2 v82, v[100:101], s[12:13] offset:96
	s_add_i32 s38, s38, 1
	s_mov_b64 s[2:3], 0
	v_readlane_b32 s6, v253, 32
	v_readlane_b32 s7, v253, 33
	s_branch .LBB0_668
